# residual-GEMM epilogue: second half's hb loads issued together with the first half's (into free VGPRs), counted waits, so they no longer queue behind the first half's stores
# baseline (speedup 1.0000x reference)
;     __device__ __forceinline__ void operator()(const f32x4 (&acc)[2][2][4][2], const Unit& u, int wr, int wc, int fr, int fq) const {
;         const int row0 = u.pm * 256 + wr * 64 + fr, col0 = u.pn * 256 + wc * 32 + 8 * fq;
;         bf16_t* hbk = hb + (size_t)(u.pn * 4 + (wc >> 1)) * M * 64 + (wc & 1) * 32 + 8 * fq; constexpr size_t BJS = (size_t)2 * M * 64;
;         const bf16_t* hrow = hbk + (size_t)row0 * 64;
; #pragma unroll
;         for (int ai = 0; ai < 2; ++ai) {
;             u32x4 bq[4][2];
; #pragma unroll
;             for (int m = 0; m < 4; ++m)
; #pragma unroll
;                 for (int bj = 0; bj < 2; ++bj) bq[m][bj] = gld<u32x4>(hrow + bj * BJS + (size_t)(ai * 128 + m * 16) * 64);
;             asm volatile("" ::: "memory");
; #pragma unroll
;             for (int m = 0; m < 4; ++m) {
;                 const int row = row0 + ai * 128 + m * 16; const size_t off = (size_t)row * D + col0; float ss = 0.f;
; #pragma unroll
;                 for (int bj = 0; bj < 2; ++bj) {
;                     const u32x4 q = bq[m][bj];
;                     const f32x4 b0 = (f32x4){bflo(q.x), bfhi(q.x), bflo(q.y), bfhi(q.y)}, b1 = (f32x4){bflo(q.z), bfhi(q.z), bflo(q.w), bfhi(q.w)};
;                     const f32x4 h0 = b0 + acc[ai][bj][m][0] * scale, h1 = b1 + acc[ai][bj][m][1] * scale;
;                     if (out32) { gst<f32x4>(out32 + off + bj * 128, h0); gst<f32x4>(out32 + off + bj * 128 + 4, h1); }
.LBB0_350:
	s_lshl_b32 s2, s53, 8
	v_readlane_b32 s3, v255, 5
	v_mov_b32_e32 v122, v232
	s_add_i32 s2, s2, s3
	v_readlane_b32 s3, v255, 31
	v_and_or_b32 v174, v122, 15, s2
	s_lshl_b32 s2, s4, 8
	v_bfe_u32 v189, v122, 4, 2
	s_or_b32 s2, s2, s3
	v_lshl_or_b32 v172, v189, 3, s2
	s_lshl_b32 s24, s4, 2
	v_readlane_b32 s2, v255, 9
	s_or_b32 s2, s24, s2
	s_ashr_i32 s3, s2, 31
	s_lshl_b64 s[2:3], s[2:3], 22
	s_add_u32 s2, s11, s2
	s_addc_u32 s3, s9, s3
	v_lshlrev_b32_e32 v122, 4, v189
	v_mov_b32_e32 v123, v96
	v_ashrrev_i32_e32 v175, 31, v174
	v_lshl_add_u64 v[122:123], s[2:3], 0, v[122:123]
	v_lshlrev_b64 v[124:125], 7, v[174:175]
	v_lshl_add_u64 v[170:171], v[122:123], 0, v[124:125]
	s_mov_b32 s2, 0x800000
	v_add_co_u32_e32 v122, vcc, s2, v170
	s_mov_b32 s2, 0x801000
	s_nop 0
	v_addc_co_u32_e32 v123, vcc, 0, v171, vcc
	v_add_co_u32_e32 v124, vcc, s2, v170
	s_movk_i32 s2, 0x1000
	s_nop 0
	v_addc_co_u32_e32 v125, vcc, 0, v171, vcc
	global_load_dwordx4 v[180:183], v[170:171], off
	global_load_dwordx4 v[154:157], v[124:125], off offset:-4096
	global_load_dwordx4 v[150:153], v[170:171], off offset:2048
	global_load_dwordx4 v[146:149], v[122:123], off offset:2048
	v_add_co_u32_e32 v122, vcc, s2, v170
	v_ashrrev_i32_e32 v173, 31, v172
	s_nop 0
	v_addc_co_u32_e32 v123, vcc, 0, v171, vcc
	global_load_dwordx4 v[142:145], v[122:123], off
	global_load_dwordx4 v[138:141], v[124:125], off
	global_load_dwordx4 v[126:129], v[122:123], off offset:2048
	s_nop 0
	global_load_dwordx4 v[122:125], v[124:125], off offset:2048
	v_add_co_u32_e32 v196, vcc, 0x4000, v170
	s_nop 1
	v_addc_co_u32_e32 v197, vcc, 0, v171, vcc
	v_add_co_u32_e32 v198, vcc, 0x804000, v170
	s_nop 1
	v_addc_co_u32_e32 v199, vcc, 0, v171, vcc
	global_load_dwordx4 v[218:221], v[196:197], off
	global_load_dwordx4 v[222:225], v[196:197], off offset:2048
	global_load_dwordx4 v[226:229], v[198:199], off
	global_load_dwordx4 v[234:237], v[198:199], off offset:2048
	v_add_co_u32_e32 v196, vcc, 0x5000, v170
	s_nop 1
	v_addc_co_u32_e32 v197, vcc, 0, v171, vcc
	v_add_co_u32_e32 v198, vcc, 0x805000, v170
	s_nop 1
	v_addc_co_u32_e32 v199, vcc, 0, v171, vcc
	global_load_dwordx4 v[238:241], v[196:197], off
	global_load_dwordx4 v[242:245], v[196:197], off offset:2048
	global_load_dwordx4 v[246:249], v[198:199], off
	global_load_dwordx4 v[192:195], v[198:199], off offset:2048
	v_lshlrev_b64 v[176:177], 10, v[174:175]
	v_lshl_add_u64 v[176:177], v[176:177], 0, v[172:173]
	s_mov_b64 s[44:45], -1
	s_andn2_b64 vcc, exec, s[16:17]
	v_lshl_add_u64 v[176:177], v[176:177], 2, s[60:61]
	s_waitcnt vmcnt(8)
	v_lshlrev_b32_e32 v178, 16, v180
	v_and_b32_e32 v179, 0xffff0000, v180
	v_lshlrev_b32_e32 v180, 16, v181
	v_and_b32_e32 v181, 0xffff0000, v181
	v_lshlrev_b32_e32 v184, 16, v182
	v_and_b32_e32 v185, 0xffff0000, v182
	v_lshlrev_b32_e32 v182, 16, v183
	v_and_b32_e32 v183, 0xffff0000, v183
	v_pk_fma_f32 v[134:135], s[30:31], v[134:135], v[178:179]
	v_cndmask_b32_e64 v178, 0, 1, s[16:17]
	v_pk_fma_f32 v[136:137], s[50:51], v[136:137], v[180:181]
	v_pk_fma_f32 v[132:133], s[50:51], v[132:133], v[182:183]
	v_pk_fma_f32 v[130:131], s[30:31], v[130:131], v[184:185]
	v_cmp_ne_u32_e64 s[42:43], 1, v178
	s_cbranch_vccnz .LBB0_352
	s_mov_b64 s[44:45], 0
	global_store_dwordx4 v[176:177], v[134:137], off
	global_store_dwordx4 v[176:177], v[130:133], off offset:16

;     __device__ __forceinline__ void operator()(const f32x4 (&acc)[2][2][4][2], const Unit& u, int wr, int wc, int fr, int fq) const {
;     ...
;         for (int ai = 0; ai < 2; ++ai) {
;             u32x4 bq[4][2];
; #pragma unroll
;             for (int m = 0; m < 4; ++m)
; #pragma unroll
;                 for (int bj = 0; bj < 2; ++bj) bq[m][bj] = gld<u32x4>(hrow + bj * BJS + (size_t)(ai * 128 + m * 16) * 64);
;             asm volatile("" ::: "memory");
; #pragma unroll
;             for (int m = 0; m < 4; ++m) {
;                 const int row = row0 + ai * 128 + m * 16; const size_t off = (size_t)row * D + col0; float ss = 0.f;
; #pragma unroll
;                 for (int bj = 0; bj < 2; ++bj) {
;                     const u32x4 q = bq[m][bj];
;                     const f32x4 b0 = (f32x4){bflo(q.x), bfhi(q.x), bflo(q.y), bfhi(q.y)}, b1 = (f32x4){bflo(q.z), bfhi(q.z), bflo(q.w), bfhi(q.w)};
;                     const f32x4 h0 = b0 + acc[ai][bj][m][0] * scale, h1 = b1 + acc[ai][bj][m][1] * scale;
;                     if (out32) { gst<f32x4>(out32 + off + bj * 128, h0); gst<f32x4>(out32 + off + bj * 128 + 4, h1); }
.LBB0_398:
	v_add_u32_e32 v92, 0x80, v174
	s_nop 0
	v_ashrrev_i32_e32 v93, 31, v92
	s_nop 0
	v_lshlrev_b64 v[94:95], 10, v[92:93]
	s_nop 0
	v_lshl_add_u64 v[94:95], v[94:95], 0, v[172:173]
	s_nop 0
	s_nop 0
	s_mov_b64 s[58:59], -1
	s_and_b64 vcc, exec, s[42:43]
	v_lshl_add_u64 v[94:95], v[94:95], 2, s[60:61]
	s_waitcnt vmcnt(8)
	v_mov_b32_e32 v98, v218
	v_mov_b32_e32 v99, v219
	v_mov_b32_e32 v100, v220
	v_mov_b32_e32 v101, v221
	v_mov_b32_e32 v84, v222
	v_mov_b32_e32 v85, v223
	v_mov_b32_e32 v86, v224
	v_mov_b32_e32 v87, v225
	v_mov_b32_e32 v88, v226
	v_mov_b32_e32 v89, v227
	v_mov_b32_e32 v90, v228
	v_mov_b32_e32 v91, v229
	v_mov_b32_e32 v80, v234
	v_mov_b32_e32 v81, v235
	v_mov_b32_e32 v82, v236
	v_mov_b32_e32 v83, v237
	v_mov_b32_e32 v76, v238
	v_mov_b32_e32 v77, v239
	v_mov_b32_e32 v78, v240
	v_mov_b32_e32 v79, v241
	v_mov_b32_e32 v68, v242
	v_mov_b32_e32 v69, v243
	v_mov_b32_e32 v70, v244
	v_mov_b32_e32 v71, v245
	v_mov_b32_e32 v72, v246
	v_mov_b32_e32 v73, v247
	v_mov_b32_e32 v74, v248
	v_mov_b32_e32 v75, v249
	v_mov_b32_e32 v64, v192
	v_mov_b32_e32 v65, v193
	v_mov_b32_e32 v66, v194
	v_mov_b32_e32 v67, v195
	v_lshlrev_b32_e32 v102, 16, v98
	v_and_b32_e32 v103, 0xffff0000, v98
	v_lshlrev_b32_e32 v98, 16, v99
	v_and_b32_e32 v99, 0xffff0000, v99
	v_lshlrev_b32_e32 v104, 16, v100
	v_and_b32_e32 v105, 0xffff0000, v100
	v_lshlrev_b32_e32 v100, 16, v101
	v_and_b32_e32 v101, 0xffff0000, v101
	v_pk_fma_f32 v[62:63], s[50:51], v[62:63], v[98:99]
	v_pk_fma_f32 v[60:61], s[30:31], v[60:61], v[102:103]
	v_pk_fma_f32 v[58:59], s[50:51], v[58:59], v[100:101]
	v_pk_fma_f32 v[56:57], s[30:31], v[56:57], v[104:105]
	s_cbranch_vccnz .LBB0_400
	s_mov_b64 s[58:59], 0
	global_store_dwordx4 v[94:95], v[60:63], off
	global_store_dwordx4 v[94:95], v[56:59], off offset:16

;     __device__ __forceinline__ void operator()(const f32x4 (&acc)[2][2][4][2], const Unit& u, int wr, int wc, int fr, int fq) const {
;     ...
;             for (int m = 0; m < 4; ++m) {
;                 const int row = row0 + ai * 128 + m * 16; const size_t off = (size_t)row * D + col0; float ss = 0.f;
; #pragma unroll
;                 for (int bj = 0; bj < 2; ++bj) {
;                     const u32x4 q = bq[m][bj];
;                     const f32x4 b0 = (f32x4){bflo(q.x), bfhi(q.x), bflo(q.y), bfhi(q.y)}, b1 = (f32x4){bflo(q.z), bfhi(q.z), bflo(q.w), bfhi(q.w)};
;                     const f32x4 h0 = b0 + acc[ai][bj][m][0] * scale, h1 = b1 + acc[ai][bj][m][1] * scale;
;                     if (out32) { gst<f32x4>(out32 + off + bj * 128, h0); gst<f32x4>(out32 + off + bj * 128 + 4, h1); }
.LBB0_402:
	s_nop 0
	v_lshlrev_b32_e32 v56, 16, v88
	v_and_b32_e32 v57, 0xffff0000, v88
	v_lshlrev_b32_e32 v58, 16, v89
	v_and_b32_e32 v59, 0xffff0000, v89
	v_lshlrev_b32_e32 v60, 16, v90
	v_and_b32_e32 v61, 0xffff0000, v90
	v_lshlrev_b32_e32 v62, 16, v91
	v_and_b32_e32 v63, 0xffff0000, v91
	v_pk_fma_f32 v[54:55], s[50:51], v[54:55], v[58:59]
	v_pk_fma_f32 v[52:53], s[30:31], v[52:53], v[56:57]
	v_pk_fma_f32 v[50:51], s[50:51], v[50:51], v[62:63]
	v_pk_fma_f32 v[48:49], s[30:31], v[48:49], v[60:61]
	s_and_b64 vcc, exec, s[42:43]
	s_mov_b64 s[58:59], -1
	s_cbranch_vccnz .LBB0_405
	global_store_dwordx4 v[94:95], v[52:55], off offset:512
	global_store_dwordx4 v[94:95], v[48:51], off offset:528
	s_cbranch_execz .LBB0_406

;     __device__ __forceinline__ void operator()(const f32x4 (&acc)[2][2][4][2], const Unit& u, int wr, int wc, int fr, int fq) const {
;     ...
;             for (int m = 0; m < 4; ++m) {
;                 const int row = row0 + ai * 128 + m * 16; const size_t off = (size_t)row * D + col0; float ss = 0.f;
; #pragma unroll
;                 for (int bj = 0; bj < 2; ++bj) {
;                     const u32x4 q = bq[m][bj];
;                     const f32x4 b0 = (f32x4){bflo(q.x), bfhi(q.x), bflo(q.y), bfhi(q.y)}, b1 = (f32x4){bflo(q.z), bfhi(q.z), bflo(q.w), bfhi(q.w)};
;                     const f32x4 h0 = b0 + acc[ai][bj][m][0] * scale, h1 = b1 + acc[ai][bj][m][1] * scale;
;                     if (out32) { gst<f32x4>(out32 + off + bj * 128, h0); gst<f32x4>(out32 + off + bj * 128 + 4, h1); }
.LBB0_414:
	s_nop 0
	v_lshlrev_b32_e32 v40, 16, v80
	v_and_b32_e32 v41, 0xffff0000, v80
	v_lshlrev_b32_e32 v42, 16, v81
	v_and_b32_e32 v43, 0xffff0000, v81
	v_lshlrev_b32_e32 v44, 16, v82
	v_and_b32_e32 v45, 0xffff0000, v82
	v_lshlrev_b32_e32 v46, 16, v83
	v_and_b32_e32 v47, 0xffff0000, v83
	v_pk_fma_f32 v[38:39], s[50:51], v[38:39], v[42:43]
	v_pk_fma_f32 v[36:37], s[30:31], v[36:37], v[40:41]
	v_pk_fma_f32 v[34:35], s[50:51], v[34:35], v[46:47]
	v_pk_fma_f32 v[32:33], s[30:31], v[32:33], v[44:45]
	s_and_b64 vcc, exec, s[42:43]
	s_mov_b64 s[58:59], -1
	s_cbranch_vccnz .LBB0_417
	global_store_dwordx4 v[50:51], v[36:39], off offset:512
	global_store_dwordx4 v[50:51], v[32:35], off offset:528
	s_cbranch_execz .LBB0_418

;     __device__ __forceinline__ void operator()(const f32x4 (&acc)[2][2][4][2], const Unit& u, int wr, int wc, int fr, int fq) const {
;     ...
;             for (int m = 0; m < 4; ++m) {
;                 const int row = row0 + ai * 128 + m * 16; const size_t off = (size_t)row * D + col0; float ss = 0.f;
; #pragma unroll
;                 for (int bj = 0; bj < 2; ++bj) {
;                     const u32x4 q = bq[m][bj];
;                     const f32x4 b0 = (f32x4){bflo(q.x), bfhi(q.x), bflo(q.y), bfhi(q.y)}, b1 = (f32x4){bflo(q.z), bfhi(q.z), bflo(q.w), bfhi(q.w)};
;                     const f32x4 h0 = b0 + acc[ai][bj][m][0] * scale, h1 = b1 + acc[ai][bj][m][1] * scale;
;                     if (out32) { gst<f32x4>(out32 + off + bj * 128, h0); gst<f32x4>(out32 + off + bj * 128 + 4, h1); }
.LBB0_422:
	v_add_u32_e32 v32, 0xa0, v174
	v_ashrrev_i32_e32 v33, 31, v32
	v_lshlrev_b64 v[34:35], 10, v[32:33]
	v_lshl_add_u64 v[34:35], v[34:35], 0, v[172:173]
	s_nop 0
	v_lshlrev_b32_e32 v36, 16, v76
	v_and_b32_e32 v37, 0xffff0000, v76
	v_lshlrev_b32_e32 v38, 16, v77
	v_and_b32_e32 v39, 0xffff0000, v77
	v_lshlrev_b32_e32 v40, 16, v78
	v_and_b32_e32 v41, 0xffff0000, v78
	v_lshlrev_b32_e32 v42, 16, v79
	v_and_b32_e32 v43, 0xffff0000, v79
	v_pk_fma_f32 v[30:31], s[50:51], v[30:31], v[38:39]
	v_pk_fma_f32 v[28:29], s[30:31], v[28:29], v[36:37]
	v_pk_fma_f32 v[26:27], s[50:51], v[26:27], v[42:43]
	v_pk_fma_f32 v[24:25], s[30:31], v[24:25], v[40:41]
	s_mov_b64 s[58:59], -1
	s_and_b64 vcc, exec, s[42:43]
	v_lshl_add_u64 v[34:35], v[34:35], 2, s[60:61]
	s_cbranch_vccnz .LBB0_424
	s_mov_b64 s[58:59], 0
	global_store_dwordx4 v[34:35], v[28:31], off
	global_store_dwordx4 v[34:35], v[24:27], off offset:16

;     __device__ __forceinline__ void operator()(const f32x4 (&acc)[2][2][4][2], const Unit& u, int wr, int wc, int fr, int fq) const {
;     ...
;             for (int m = 0; m < 4; ++m) {
;                 const int row = row0 + ai * 128 + m * 16; const size_t off = (size_t)row * D + col0; float ss = 0.f;
; #pragma unroll
;                 for (int bj = 0; bj < 2; ++bj) {
;                     const u32x4 q = bq[m][bj];
;                     const f32x4 b0 = (f32x4){bflo(q.x), bfhi(q.x), bflo(q.y), bfhi(q.y)}, b1 = (f32x4){bflo(q.z), bfhi(q.z), bflo(q.w), bfhi(q.w)};
;                     const f32x4 h0 = b0 + acc[ai][bj][m][0] * scale, h1 = b1 + acc[ai][bj][m][1] * scale;
;                     if (out32) { gst<f32x4>(out32 + off + bj * 128, h0); gst<f32x4>(out32 + off + bj * 128 + 4, h1); }
.LBB0_426:
	s_nop 0
	v_lshlrev_b32_e32 v24, 16, v72
	v_and_b32_e32 v25, 0xffff0000, v72
	v_lshlrev_b32_e32 v26, 16, v73
	v_and_b32_e32 v27, 0xffff0000, v73
	v_lshlrev_b32_e32 v28, 16, v74
	v_and_b32_e32 v29, 0xffff0000, v74
	v_lshlrev_b32_e32 v30, 16, v75
	v_and_b32_e32 v31, 0xffff0000, v75
	v_pk_fma_f32 v[22:23], s[50:51], v[22:23], v[26:27]
	v_pk_fma_f32 v[20:21], s[30:31], v[20:21], v[24:25]
	v_pk_fma_f32 v[18:19], s[50:51], v[18:19], v[30:31]
	v_pk_fma_f32 v[16:17], s[30:31], v[16:17], v[28:29]
	s_and_b64 vcc, exec, s[42:43]
	s_mov_b64 s[58:59], -1
	s_cbranch_vccnz .LBB0_429
	global_store_dwordx4 v[34:35], v[20:23], off offset:512
	global_store_dwordx4 v[34:35], v[16:19], off offset:528
	s_cbranch_execz .LBB0_430

;     __device__ __forceinline__ void operator()(const f32x4 (&acc)[2][2][4][2], const Unit& u, int wr, int wc, int fr, int fq) const {
;     ...
;             for (int m = 0; m < 4; ++m) {
;                 const int row = row0 + ai * 128 + m * 16; const size_t off = (size_t)row * D + col0; float ss = 0.f;
; #pragma unroll
;                 for (int bj = 0; bj < 2; ++bj) {
;                     const u32x4 q = bq[m][bj];
;                     const f32x4 b0 = (f32x4){bflo(q.x), bfhi(q.x), bflo(q.y), bfhi(q.y)}, b1 = (f32x4){bflo(q.z), bfhi(q.z), bflo(q.w), bfhi(q.w)};
;                     const f32x4 h0 = b0 + acc[ai][bj][m][0] * scale, h1 = b1 + acc[ai][bj][m][1] * scale;
;                     if (out32) { gst<f32x4>(out32 + off + bj * 128, h0); gst<f32x4>(out32 + off + bj * 128 + 4, h1); }
.LBB0_438:
	s_nop 0
	v_lshlrev_b32_e32 v8, 16, v64
	v_and_b32_e32 v9, 0xffff0000, v64
	v_lshlrev_b32_e32 v10, 16, v65
	v_and_b32_e32 v11, 0xffff0000, v65
	v_lshlrev_b32_e32 v12, 16, v66
	v_and_b32_e32 v13, 0xffff0000, v66
	v_lshlrev_b32_e32 v14, 16, v67
	v_and_b32_e32 v15, 0xffff0000, v67
	v_pk_fma_f32 v[6:7], s[50:51], v[6:7], v[10:11]
	v_pk_fma_f32 v[4:5], s[30:31], v[4:5], v[8:9]
	v_pk_fma_f32 v[2:3], s[50:51], v[2:3], v[14:15]
	v_pk_fma_f32 v[0:1], s[30:31], v[0:1], v[12:13]
	s_and_b64 vcc, exec, s[42:43]
	s_mov_b64 s[42:43], -1
	s_cbranch_vccnz .LBB0_441
	global_store_dwordx4 v[18:19], v[4:7], off offset:512
	global_store_dwordx4 v[18:19], v[0:3], off offset:528
	s_cbranch_execz .LBB0_442
